# sc1 (write-through) stores in P0
# speedup vs baseline: 1.0148x; 1.0049x over previous
; #define LAS __attribute__((address_space(3)))
; __device__ __forceinline__ void p0_prologue(const Ptrs& P, LAS unsigned char* lds, int vcu, int G, int tid) {
;     ...
;                 for (int j = 0; j < 4; ++j) { const int n = (lane >> 3) + 8 * j; const LAS float* sp = scr + (8 * c) * 33 + n;
;                     u32x4 o; o.x = pkg(sp[0 * 33], sp[1 * 33]); o.y = pkg(sp[2 * 33], sp[3 * 33]); o.z = pkg(sp[4 * 33], sp[5 * 33]); o.w = pkg(sp[6 * 33], sp[7 * 33]);
;                     *(u32x4*)(cur.dst + (size_t)n * cur.ldk + 8 * c) = o; }
.LBB0_37:
	ds_read2_b32 v[6:7], v84 offset0:24 offset1:33
	ds_read2_b32 v[8:9], v84 offset0:57 offset1:66
	ds_read2_b32 v[10:11], v84 offset0:90 offset1:99
	ds_read2_b32 v[12:13], v84 offset0:123 offset1:132
	ds_read2_b32 v[14:15], v84 offset0:156 offset1:165
	ds_read2_b32 v[16:17], v84 offset0:189 offset1:198
	ds_read2_b32 v[18:19], v84 offset0:222 offset1:231
	ds_read2_b32 v[24:25], v84 offset0:8 offset1:16
	ds_read2_b32 v[26:27], v84 offset0:41 offset1:49
	ds_read2_b32 v[28:29], v84 offset0:74 offset1:82
	ds_read2_b32 v[30:31], v84 offset0:107 offset1:115
	ds_read2_b32 v[32:33], v84 offset0:140 offset1:148
	ds_read2_b32 v[78:79], v84 offset0:173 offset1:181
	ds_read2_b32 v[86:87], v84 offset0:206 offset1:214
	ds_read2_b32 v[88:89], v84 offset0:239 offset1:247
	v_lshlrev_b32_e32 v68, 1, v66
	v_lshl_add_u64 v[20:21], s[18:19], 0, v[68:69]
	v_lshlrev_b32_e32 v68, 1, v70
	s_waitcnt lgkmcnt(14)
	v_cvt_pk_bf16_f32 v2, v2, v7
	s_waitcnt lgkmcnt(8)
	v_cvt_pk_bf16_f32 v5, v17, v19
	v_lshl_add_u64 v[22:23], v[20:21], 0, v[68:69]
	v_lshlrev_b32_e32 v68, 1, v72
	v_cvt_pk_bf16_f32 v3, v9, v11
	v_cvt_pk_bf16_f32 v4, v13, v15
	global_store_dwordx4 v[22:23], v[2:5], off sc1
	v_lshl_add_u64 v[22:23], v[20:21], 0, v[68:69]
	v_lshlrev_b32_e32 v68, 1, v74
	s_waitcnt lgkmcnt(6)
	v_cvt_pk_bf16_f32 v2, v24, v26
	s_waitcnt lgkmcnt(0)
	v_cvt_pk_bf16_f32 v5, v86, v88
	v_cvt_pk_bf16_f32 v3, v28, v30
	v_cvt_pk_bf16_f32 v4, v32, v78
	global_store_dwordx4 v[22:23], v[2:5], off sc1
	v_lshl_add_u64 v[22:23], v[20:21], 0, v[68:69]
	ds_read_b32 v7, v84 offset:1020
	v_cvt_pk_bf16_f32 v2, v25, v27
	v_cvt_pk_bf16_f32 v5, v87, v89
	v_lshlrev_b32_e32 v68, 1, v76
	v_cvt_pk_bf16_f32 v3, v29, v31
	v_cvt_pk_bf16_f32 v4, v33, v79
	global_store_dwordx4 v[22:23], v[2:5], off sc1
	s_nop 1
	v_cvt_pk_bf16_f32 v2, v6, v8
	s_waitcnt lgkmcnt(0)
	v_cvt_pk_bf16_f32 v5, v18, v7
	v_lshl_add_u64 v[6:7], v[20:21], 0, v[68:69]
	v_cvt_pk_bf16_f32 v3, v10, v12
	v_cvt_pk_bf16_f32 v4, v14, v16
	global_store_dwordx4 v[6:7], v[2:5], off sc1

; #define LAS __attribute__((address_space(3)))
; __device__ __forceinline__ void p0_prologue(const Ptrs& P, LAS unsigned char* lds, int vcu, int G, int tid) {
;     ...
;             const int nit = it + NGW; const bool has_n = nit < NITEMS;
;             f32x4 nv[8];
;             const TItem nxt = t_decode(P, has_n ? nit : it, lane); t_load(nxt, nv);
;             const int c4 = 4 * (lane & 7), r8 = lane >> 3;
; #pragma unroll
;             for (int j = 0; j < 8; ++j) { LAS float* d = scr + (8 * j + r8) * 33 + c4; d[0] = v[j][0]; d[1] = v[j][1]; d[2] = v[j][2]; d[3] = v[j][3]; }
;             asm volatile("s_waitcnt lgkmcnt(0)" ::: "memory");
;             const int c = lane & 7;
;             if (cur.f8) {
; #pragma unroll
;                 for (int j = 0; j < 4; ++j) { const int n = (lane >> 3) + 8 * j; const LAS float* sp = scr + (8 * c) * 33 + n;
;                     int w0 = 0, w1 = 0;
;                     w0 = __builtin_amdgcn_cvt_pk_fp8_f32(sp[0 * 33] * F8_SW, sp[1 * 33] * F8_SW, w0, false); w0 = __builtin_amdgcn_cvt_pk_fp8_f32(sp[2 * 33] * F8_SW, sp[3 * 33] * F8_SW, w0, true);
;                     w1 = __builtin_amdgcn_cvt_pk_fp8_f32(sp[4 * 33] * F8_SW, sp[5 * 33] * F8_SW, w1, false); w1 = __builtin_amdgcn_cvt_pk_fp8_f32(sp[6 * 33] * F8_SW, sp[7 * 33] * F8_SW, w1, true);
;                     u32x2 o; o.x = (unsigned)w0; o.y = (unsigned)w1;
;                     *(u32x2*)((unsigned char*)cur.dst + (size_t)n * cur.ldk + 8 * c) = o; }
.LBB0_62:
	s_lshl_b32 s20, s26, 5
	v_lshl_add_u64 v[42:43], v[78:79], 0, s[20:21]
	v_lshl_add_u64 v[44:45], v[42:43], 0, s[20:21]
	v_lshl_add_u64 v[50:51], v[44:45], 0, s[20:21]
	v_lshl_add_u64 v[52:53], v[50:51], 0, s[20:21]
	v_lshl_add_u64 v[58:59], v[52:53], 0, s[20:21]
	v_lshl_add_u64 v[60:61], v[58:59], 0, s[20:21]
	global_load_dwordx4 v[34:37], v[42:43], off nt
	global_load_dwordx4 v[38:41], v[44:45], off nt
	s_nop 0
	global_load_dwordx4 v[42:45], v[50:51], off nt
	global_load_dwordx4 v[46:49], v[52:53], off nt
	s_nop 0
	global_load_dwordx4 v[50:53], v[58:59], off nt
	global_load_dwordx4 v[54:57], v[60:61], off nt
	v_lshl_add_u64 v[86:87], v[60:61], 0, s[20:21]
	global_load_dwordx4 v[62:65], v[78:79], off nt
	global_load_dwordx4 v[58:61], v[86:87], off nt
	s_waitcnt vmcnt(12)
	ds_write2_b32 v85, v30, v31 offset1:1
	ds_write2_b32 v85, v32, v33 offset0:2 offset1:3
	v_add_u32_e32 v30, 0x420, v85
	ds_write2_b32 v30, v26, v27 offset1:1
	v_add_u32_e32 v26, 0x428, v85
	ds_write2_b32 v26, v28, v29 offset1:1
	v_add_u32_e32 v26, 0x840, v85
	ds_write2_b32 v26, v22, v23 offset1:1
	v_add_u32_e32 v22, 0x848, v85
	ds_write2_b32 v22, v24, v25 offset1:1
	v_add_u32_e32 v22, 0xc60, v85
	ds_write2_b32 v22, v18, v19 offset1:1
	v_add_u32_e32 v18, 0xc68, v85
	ds_write2_b32 v18, v20, v21 offset1:1
	v_add_u32_e32 v18, 0x1080, v85
	ds_write2_b32 v18, v14, v15 offset1:1
	v_add_u32_e32 v14, 0x1088, v85
	ds_write2_b32 v14, v16, v17 offset1:1
	v_add_u32_e32 v14, 0x14a0, v85
	ds_write2_b32 v14, v10, v11 offset1:1
	v_add_u32_e32 v10, 0x14a8, v85
	ds_write2_b32 v10, v12, v13 offset1:1
	v_add_u32_e32 v10, 0x18c0, v85
	ds_write2_b32 v10, v6, v7 offset1:1
	v_add_u32_e32 v6, 0x18c8, v85
	ds_write2_b32 v6, v8, v9 offset1:1
	v_add_u32_e32 v6, 0x1ce0, v85
	ds_write2_b32 v6, v2, v3 offset1:1
	v_add_u32_e32 v2, 0x1ce8, v85
	ds_write2_b32 v2, v4, v5 offset1:1
	s_waitcnt lgkmcnt(0)
	ds_read_b32 v2, v84
	s_cmp_eq_u32 s51, 0
	s_cbranch_scc1 .LBB0_64
	ds_read2_b32 v[4:5], v84 offset0:24 offset1:33
	ds_read2_b32 v[10:11], v84 offset0:57 offset1:66
	ds_read2_b32 v[12:13], v84 offset0:90 offset1:99
	s_waitcnt lgkmcnt(3)
	v_mul_f32_e32 v3, 0x43800000, v2
	v_mov_b32_e32 v8, v69
	s_waitcnt lgkmcnt(2)
	v_mul_f32_e32 v5, 0x43800000, v5
	ds_read2_b32 v[14:15], v84 offset0:123 offset1:132
	ds_read2_b32 v[16:17], v84 offset0:156 offset1:165
	v_cvt_pk_fp8_f32 v8, v3, v5
	s_waitcnt lgkmcnt(3)
	v_mul_f32_e32 v3, 0x43800000, v11
	s_waitcnt lgkmcnt(2)
	v_mul_f32_e32 v5, 0x43800000, v13
	ds_read2_b32 v[18:19], v84 offset0:189 offset1:198
	ds_read2_b32 v[20:21], v84 offset0:222 offset1:231
	v_cvt_pk_fp8_f32 v8, v3, v5 op_sel:[0,0,1]
	s_waitcnt lgkmcnt(3)
	v_mul_f32_e32 v3, 0x43800000, v15
	s_waitcnt lgkmcnt(2)
	v_mul_f32_e32 v5, 0x43800000, v17
	v_mov_b32_e32 v9, v69
	ds_read2_b32 v[22:23], v84 offset0:8 offset1:16
	ds_read2_b32 v[24:25], v84 offset0:41 offset1:49
	v_cvt_pk_fp8_f32 v9, v3, v5
	ds_read2_b32 v[28:29], v84 offset0:74 offset1:82
	ds_read2_b32 v[30:31], v84 offset0:107 offset1:115
	ds_read2_b32 v[32:33], v84 offset0:140 offset1:148
	ds_read2_b32 v[78:79], v84 offset0:173 offset1:181
	s_waitcnt lgkmcnt(7)
	v_mul_f32_e32 v3, 0x43800000, v19
	s_waitcnt lgkmcnt(6)
	v_mul_f32_e32 v5, 0x43800000, v21
	v_cvt_pk_fp8_f32 v9, v3, v5 op_sel:[0,0,1]
	s_waitcnt lgkmcnt(5)
	v_mul_f32_e32 v3, 0x43800000, v22
	s_waitcnt lgkmcnt(4)
	v_mul_f32_e32 v5, 0x43800000, v24
	v_mov_b32_e32 v26, v69
	ds_read2_b32 v[86:87], v84 offset0:206 offset1:214
	ds_read2_b32 v[88:89], v84 offset0:239 offset1:247
	v_cvt_pk_fp8_f32 v26, v3, v5
	s_waitcnt lgkmcnt(3)
	v_mul_f32_e32 v11, 0x43800000, v32
	s_waitcnt lgkmcnt(2)
	v_mul_f32_e32 v13, 0x43800000, v78
	v_mov_b32_e32 v27, v69
	v_cvt_pk_fp8_f32 v27, v11, v13
	v_mul_f32_e32 v3, 0x43800000, v28
	v_mul_f32_e32 v5, 0x43800000, v30
	v_cvt_pk_fp8_f32 v26, v3, v5 op_sel:[0,0,1]
	s_waitcnt lgkmcnt(1)
	v_mul_f32_e32 v3, 0x43800000, v86
	s_waitcnt lgkmcnt(0)
	v_mul_f32_e32 v5, 0x43800000, v88
	v_cvt_pk_fp8_f32 v27, v3, v5 op_sel:[0,0,1]
	v_lshl_add_u64 v[6:7], s[18:19], 0, v[66:67]
	v_lshl_add_u64 v[92:93], v[6:7], 0, v[70:71]
	global_store_dwordx2 v[92:93], v[8:9], off sc1
	v_lshl_add_u64 v[8:9], v[6:7], 0, v[72:73]
	global_store_dwordx2 v[8:9], v[26:27], off sc1
	v_mul_f32_e32 v3, 0x43800000, v23
	v_mul_f32_e32 v5, 0x43800000, v25
	v_mov_b32_e32 v8, v69
	v_cvt_pk_fp8_f32 v8, v3, v5
	v_mul_f32_e32 v11, 0x43800000, v33
	v_mul_f32_e32 v13, 0x43800000, v79
	v_mov_b32_e32 v9, v69
	v_cvt_pk_fp8_f32 v9, v11, v13
	v_mul_f32_e32 v3, 0x43800000, v29
	v_mul_f32_e32 v5, 0x43800000, v31
	v_cvt_pk_fp8_f32 v8, v3, v5 op_sel:[0,0,1]
	v_mul_f32_e32 v3, 0x43800000, v87
	v_mul_f32_e32 v5, 0x43800000, v89
	v_cvt_pk_fp8_f32 v9, v3, v5 op_sel:[0,0,1]
	v_mul_f32_e32 v3, 0x43800000, v4
	v_mul_f32_e32 v5, 0x43800000, v10
	v_mov_b32_e32 v4, v69
	ds_read_b32 v13, v84 offset:1020
	v_cvt_pk_fp8_f32 v4, v3, v5
	v_mul_f32_e32 v3, 0x43800000, v12
	v_mul_f32_e32 v11, 0x43800000, v16
	v_mul_f32_e32 v12, 0x43800000, v18
	v_mov_b32_e32 v5, v69
	v_cvt_pk_fp8_f32 v5, v11, v12
	v_mul_f32_e32 v10, 0x43800000, v14
	v_cvt_pk_fp8_f32 v4, v3, v10 op_sel:[0,0,1]
	v_mul_f32_e32 v3, 0x43800000, v20
	s_waitcnt lgkmcnt(0)
	v_mul_f32_e32 v10, 0x43800000, v13
	v_cvt_pk_fp8_f32 v5, v3, v10 op_sel:[0,0,1]
	v_lshl_add_u64 v[10:11], v[6:7], 0, v[74:75]
	v_lshl_add_u64 v[6:7], v[6:7], 0, v[76:77]
	global_store_dwordx2 v[10:11], v[8:9], off sc1
	global_store_dwordx2 v[6:7], v[4:5], off sc1
	s_cbranch_execnz .LBB0_38
	s_branch .LBB0_37

; __device__ __forceinline__ void p0_prologue(const Ptrs& P, LAS unsigned char* lds, int vcu, int G, int tid) {
;     ...
;         for (int m = gw; m < T; m += NGW) {
;             const f32x4* xr = (const f32x4*)(P.x + (size_t)m * D) + lane;
;             f32x4 v[16]; float s = 0.f;
; #pragma unroll
;             for (int j = 0; j < 16; ++j) v[j] = __builtin_nontemporal_load(xr + 64 * j);
; #pragma unroll
;             for (int j = 0; j < 16; ++j) s += (v[j][0] * v[j][0] + v[j][1] * v[j][1]) + (v[j][2] * v[j][2] + v[j][3] * v[j][3]);
.LBB0_67:
	global_load_dwordx4 v[78:81], v[82:83], off nt
	global_load_dwordx4 v[74:77], v[82:83], off offset:1024 nt
	global_load_dwordx4 v[70:73], v[82:83], off offset:3072 nt
	global_load_dwordx4 v[66:69], v[82:83], off offset:2048 nt
	v_add_co_u32_e32 v88, vcc, 0x1000, v82
	v_mov_b32_e32 v98, 0
	s_nop 0
	v_addc_co_u32_e32 v89, vcc, 0, v83, vcc
	global_load_dwordx4 v[114:117], v[88:89], off nt
	global_load_dwordx4 v[118:121], v[88:89], off offset:2048 nt
	global_load_dwordx4 v[122:125], v[88:89], off offset:1024 nt
	global_load_dwordx4 v[126:129], v[88:89], off offset:3072 nt
	v_add_co_u32_e32 v142, vcc, s15, v82
	v_mov_b32_e32 v99, 0
	s_nop 0
	v_addc_co_u32_e32 v143, vcc, 0, v83, vcc
	global_load_dwordx4 v[130:133], v[142:143], off offset:1024 nt
	global_load_dwordx4 v[134:137], v[142:143], off offset:2048 nt
	v_add_co_u32_e32 v88, vcc, s14, v82
	v_mov_b32_e32 v100, 0
	s_nop 0
	v_addc_co_u32_e32 v89, vcc, 0, v83, vcc
	global_load_dwordx4 v[138:141], v[88:89], off offset:-4096 nt
	s_nop 0
	global_load_dwordx4 v[142:145], v[142:143], off offset:3072 nt
	s_nop 0
	global_load_dwordx4 v[146:149], v[88:89], off nt
	global_load_dwordx4 v[150:153], v[88:89], off offset:1024 nt
	global_load_dwordx4 v[154:157], v[88:89], off offset:2048 nt
	global_load_dwordx4 v[158:161], v[88:89], off offset:3072 nt
	v_mov_b32_e32 v101, 0
	v_mov_b32_e32 v102, 0
	v_mov_b32_e32 v103, 0
	v_mov_b32_e32 v104, 0
	v_mov_b32_e32 v105, 0
	v_mov_b32_e32 v106, 0
	v_mov_b32_e32 v107, 0
	v_mov_b32_e32 v108, 0
	v_mov_b32_e32 v109, 0
	v_mov_b32_e32 v110, 0
	v_mov_b32_e32 v111, 0
	v_mov_b32_e32 v112, 0
	v_mov_b32_e32 v113, 0
	s_add_i32 s3, s3, s0
	s_cmpk_gt_i32 s3, 0x1fff
	v_lshl_add_u64 v[82:83], v[82:83], 0, s[6:7]
	s_waitcnt vmcnt(15)
	v_pk_mul_f32 v[88:89], v[80:81], v[80:81]
	v_pk_mul_f32 v[162:163], v[78:79], v[78:79]
	s_waitcnt vmcnt(14)
	v_pk_mul_f32 v[164:165], v[76:77], v[76:77]
	v_pk_mul_f32 v[166:167], v[74:75], v[74:75]
	s_waitcnt vmcnt(13)
	v_mul_f32_e32 v169, v70, v70
	v_mul_f32_e32 v171, v71, v71
	v_mul_f32_e32 v172, v72, v72
	v_mul_f32_e32 v173, v73, v73
	v_mul_f32_e32 v186, v50, v70
	v_mul_f32_e32 v187, v51, v71
	v_mul_f32_e32 v188, v52, v72
	v_mul_f32_e32 v189, v53, v73
	v_pk_mov_b32 v[70:71], v[162:163], v[88:89] op_sel:[1,0]
	v_mov_b32_e32 v163, v89
	v_pk_mov_b32 v[72:73], v[166:167], v[164:165] op_sel:[1,0]
	v_mov_b32_e32 v167, v165
	s_waitcnt vmcnt(12)
	v_mul_f32_e32 v168, v67, v67
	v_mul_f32_e32 v170, v69, v69
	v_pk_add_f32 v[70:71], v[70:71], v[162:163]
	v_pk_add_f32 v[72:73], v[72:73], v[166:167]
	v_mul_f32_e32 v182, v54, v66
	v_mul_f32_e32 v183, v55, v67
	v_mul_f32_e32 v184, v56, v68
	v_mul_f32_e32 v185, v57, v69
	v_pk_fma_f32 v[66:67], v[66:67], v[66:67], v[168:169] op_sel_hi:[1,1,0]
	v_pk_fma_f32 v[68:69], v[68:69], v[68:69], v[170:171] op_sel_hi:[1,1,0]
	v_pk_add_f32 v[70:71], v[70:71], v[70:71] op_sel:[0,1] op_sel_hi:[1,0]
	v_pk_add_f32 v[72:73], v[72:73], v[72:73] op_sel:[0,1] op_sel_hi:[1,0]
	v_mul_f32_e32 v178, v58, v74
	v_mul_f32_e32 v179, v59, v75
	v_mul_f32_e32 v180, v60, v76
	v_mul_f32_e32 v181, v61, v77
	v_mov_b32_e32 v67, v172
	v_mov_b32_e32 v69, v173
	s_waitcnt vmcnt(11)
	v_pk_mul_f32 v[74:75], v[116:117], v[116:117]
	v_pk_mul_f32 v[76:77], v[114:115], v[114:115]
	v_mov_b32_e32 v71, v169
	v_mov_b32_e32 v73, v171
	v_pk_add_f32 v[66:67], v[66:67], v[68:69]
	v_pk_mov_b32 v[68:69], v[76:77], v[74:75] op_sel:[1,0]
	v_mov_b32_e32 v77, v75
	v_pk_add_f32 v[70:71], v[70:71], v[72:73]
	v_mul_f32_e32 v174, v62, v78
	v_mul_f32_e32 v176, v64, v80
	s_waitcnt vmcnt(9)
	v_mul_f32_e32 v78, v123, v123
	v_mul_f32_e32 v80, v125, v125
	v_pk_add_f32 v[68:69], v[68:69], v[76:77]
	v_pk_add_f32 v[66:67], v[70:71], v[66:67]
	v_mul_f32_e32 v175, v63, v79
	v_mul_f32_e32 v164, v118, v118
	v_mul_f32_e32 v165, v119, v119
	v_mul_f32_e32 v166, v120, v120
	v_mul_f32_e32 v167, v121, v121
	v_pk_fma_f32 v[74:75], v[122:123], v[122:123], v[78:79] op_sel_hi:[1,1,0]
	v_pk_fma_f32 v[78:79], v[124:125], v[124:125], v[80:81] op_sel_hi:[1,1,0]
	v_pk_add_f32 v[68:69], v[68:69], v[68:69] op_sel:[0,1] op_sel_hi:[1,0]
	v_pk_add_f32 v[66:67], v[66:67], v[66:67] op_sel:[0,1] op_sel_hi:[1,0]
	s_waitcnt vmcnt(8)
	v_pk_mul_f32 v[88:89], v[128:129], v[128:129]
	v_pk_mul_f32 v[162:163], v[126:127], v[126:127]
	v_mov_b32_e32 v75, v166
	v_mov_b32_e32 v79, v167
	v_mov_b32_e32 v69, v165
	v_mov_b32_e32 v67, v164
	v_mul_f32_e32 v177, v65, v81
	v_pk_mov_b32 v[80:81], v[162:163], v[88:89] op_sel:[1,0]
	v_mov_b32_e32 v163, v89
	v_pk_add_f32 v[72:73], v[74:75], v[78:79]
	v_pk_add_f32 v[66:67], v[66:67], v[68:69]
	v_mul_f32_e32 v172, v48, v116
	v_pk_add_f32 v[76:77], v[80:81], v[162:163]
	s_waitcnt vmcnt(5)
	v_mul_f32_e32 v80, v139, v139
	v_mul_f32_e32 v116, v141, v141
	v_pk_add_f32 v[66:67], v[66:67], v[72:73]
	v_mul_f32_e32 v200, v130, v130
	v_mul_f32_e32 v201, v131, v131
	v_mul_f32_e32 v202, v132, v132
	v_mul_f32_e32 v203, v133, v133
	v_pk_add_f32 v[74:75], v[76:77], v[76:77] op_sel:[0,1] op_sel_hi:[1,0]
	v_pk_fma_f32 v[76:77], v[138:139], v[138:139], v[80:81] op_sel_hi:[1,1,0]
	v_pk_fma_f32 v[78:79], v[140:141], v[140:141], v[116:117] op_sel_hi:[1,1,0]
	v_pk_add_f32 v[66:67], v[66:67], v[66:67] op_sel:[0,1] op_sel_hi:[1,0]
	v_mul_f32_e32 v168, v46, v114
	v_mul_f32_e32 v170, v47, v115
	v_pk_mul_f32 v[88:89], v[136:137], v[136:137]
	v_pk_mul_f32 v[114:115], v[134:135], v[134:135]
	v_mov_b32_e32 v75, v201
	v_mov_b32_e32 v77, v202
	v_mov_b32_e32 v79, v203
	v_mov_b32_e32 v67, v200
	v_mul_f32_e32 v194, v38, v118
	v_mul_f32_e32 v195, v39, v119
	v_pk_mov_b32 v[118:119], v[114:115], v[88:89] op_sel:[1,0]
	v_mov_b32_e32 v115, v89
	v_pk_add_f32 v[76:77], v[76:77], v[78:79]
	v_pk_add_f32 v[66:67], v[66:67], v[74:75]
	v_mul_f32_e32 v196, v40, v120
	s_waitcnt vmcnt(4)
; __device__ __forceinline__ void p0_prologue(const Ptrs& P, LAS unsigned char* lds, int vcu, int G, int tid) {
;     ...
;             for (int j = 0; j < 16; ++j) s += (v[j][0] * v[j][0] + v[j][1] * v[j][1]) + (v[j][2] * v[j][2] + v[j][3] * v[j][3]);
;             const float rs = rsqrtf(wave_sum(s) * (1.f / D) + EPS), s8 = rs * F8_SU;
;             u32x2* o = (u32x2*)(P.U + (size_t)m * D) + lane;
;             unsigned* o8 = (unsigned*)(P.U8 + (size_t)m * D) + lane;
; #pragma unroll
;             for (int j = 0; j < 16; ++j) { const f32x4 w = nwv[j]; const float a0 = v[j][0] * w[0], a1 = v[j][1] * w[1], a2 = v[j][2] * w[2], a3 = v[j][3] * w[3];
;                 u32x2 q; q.x = pkg(a0 * rs, a1 * rs); q.y = pkg(a2 * rs, a3 * rs); o[64 * j] = q;
;                 int w8 = 0; w8 = __builtin_amdgcn_cvt_pk_fp8_f32(a0 * s8, a1 * s8, w8, false); w8 = __builtin_amdgcn_cvt_pk_fp8_f32(a2 * s8, a3 * s8, w8, true); o8[64 * j] = (unsigned)w8; }
	v_mul_f32_e32 v88, v143, v143
	v_mul_f32_e32 v120, v145, v145
	v_pk_add_f32 v[80:81], v[118:119], v[114:115]
	v_pk_add_f32 v[66:67], v[66:67], v[76:77]
	s_waitcnt vmcnt(3)
	v_mul_f32_e32 v162, v146, v146
	v_mul_f32_e32 v163, v147, v147
	v_mul_f32_e32 v166, v148, v148
	v_mul_f32_e32 v167, v149, v149
	v_pk_fma_f32 v[88:89], v[142:143], v[142:143], v[88:89] op_sel_hi:[1,1,0]
	v_pk_fma_f32 v[114:115], v[144:145], v[144:145], v[120:121] op_sel_hi:[1,1,0]
	v_pk_add_f32 v[70:71], v[80:81], v[80:81] op_sel:[0,1] op_sel_hi:[1,0]
	v_pk_add_f32 v[66:67], v[66:67], v[66:67] op_sel:[0,1] op_sel_hi:[1,0]
	v_mul_f32_e32 v190, v42, v122
	v_mul_f32_e32 v191, v43, v123
	v_mul_f32_e32 v192, v44, v124
	v_mul_f32_e32 v193, v45, v125
	s_waitcnt vmcnt(2)
	v_pk_mul_f32 v[122:123], v[152:153], v[152:153]
	v_pk_mul_f32 v[124:125], v[150:151], v[150:151]
	v_mov_b32_e32 v89, v166
	v_mov_b32_e32 v115, v167
	v_mov_b32_e32 v71, v163
	v_mov_b32_e32 v67, v162
	v_mul_f32_e32 v173, v49, v117
	v_pk_mov_b32 v[116:117], v[124:125], v[122:123] op_sel:[1,0]
	v_mov_b32_e32 v125, v123
	v_pk_add_f32 v[78:79], v[88:89], v[114:115]
	v_pk_add_f32 v[66:67], v[66:67], v[70:71]
	v_mul_f32_e32 v198, v34, v126
	v_mul_f32_e32 v127, v35, v127
	v_mul_f32_e32 v199, v36, v128
	v_mul_f32_e32 v129, v37, v129
	s_waitcnt vmcnt(1)
	v_mul_f32_e32 v126, v155, v155
	v_mul_f32_e32 v128, v157, v157
	v_pk_add_f32 v[80:81], v[116:117], v[124:125]
	v_pk_add_f32 v[66:67], v[66:67], v[78:79]
	v_mul_f32_e32 v197, v41, v121
	s_waitcnt vmcnt(0)
	v_mul_f32_e32 v169, v158, v158
	v_mul_f32_e32 v171, v159, v159
	v_mul_f32_e32 v204, v160, v160
	v_mul_f32_e32 v205, v161, v161
	v_pk_fma_f32 v[118:119], v[154:155], v[154:155], v[126:127] op_sel_hi:[1,1,0]
	v_pk_fma_f32 v[120:121], v[156:157], v[156:157], v[128:129] op_sel_hi:[1,1,0]
	v_pk_add_f32 v[80:81], v[80:81], v[80:81] op_sel:[0,1] op_sel_hi:[1,0]
	v_pk_add_f32 v[66:67], v[66:67], v[66:67] op_sel:[0,1] op_sel_hi:[1,0]
	v_mov_b32_e32 v119, v204
	v_mov_b32_e32 v121, v205
	v_mov_b32_e32 v81, v171
	v_mov_b32_e32 v67, v169
	v_pk_add_f32 v[88:89], v[118:119], v[120:121]
	v_pk_add_f32 v[66:67], v[66:67], v[80:81]
	v_mul_f32_e32 v130, v26, v130
	v_pk_add_f32 v[66:67], v[66:67], v[88:89]
	v_mul_f32_e32 v131, v27, v131
	v_add_f32_e32 v66, v66, v67
	ds_bpermute_b32 v67, v91, v66
	v_mul_f32_e32 v134, v22, v134
	v_mul_f32_e32 v135, v23, v135
	v_mul_f32_e32 v206, v30, v138
	v_mul_f32_e32 v207, v31, v139
	s_waitcnt lgkmcnt(0)
	v_add_f32_e32 v66, v66, v67
	ds_bpermute_b32 v67, v92, v66
	v_mul_f32_e32 v132, v28, v132
	v_mul_f32_e32 v133, v29, v133
	v_mul_f32_e32 v136, v24, v136
	v_mul_f32_e32 v137, v25, v137
	s_waitcnt lgkmcnt(0)
	v_add_f32_e32 v66, v66, v67
	ds_bpermute_b32 v67, v93, v66
	v_mul_f32_e32 v208, v32, v140
	v_mul_f32_e32 v209, v33, v141
	v_mul_f32_e32 v210, v18, v142
	v_mul_f32_e32 v211, v19, v143
	s_waitcnt lgkmcnt(0)
	v_add_f32_e32 v66, v66, v67
	ds_bpermute_b32 v67, v94, v66
	v_mul_f32_e32 v213, v20, v144
	v_mul_f32_e32 v214, v21, v145
	v_mul_f32_e32 v146, v14, v146
	v_mul_f32_e32 v147, v15, v147
	s_waitcnt lgkmcnt(0)
	v_add_f32_e32 v66, v66, v67
	ds_bpermute_b32 v67, v95, v66
	v_mul_f32_e32 v148, v16, v148
	v_mul_f32_e32 v149, v17, v149
	v_mul_f32_e32 v150, v10, v150
	v_mul_f32_e32 v151, v11, v151
	s_waitcnt lgkmcnt(0)
	v_add_f32_e32 v66, v66, v67
	ds_bpermute_b32 v67, v96, v66
	v_mul_f32_e32 v152, v12, v152
	v_mul_f32_e32 v153, v13, v153
	v_mul_f32_e32 v215, v6, v154
	v_mul_f32_e32 v216, v7, v155
	s_waitcnt lgkmcnt(0)
	v_add_f32_e32 v66, v66, v67
	v_fmamk_f32 v66, v66, 0x39800000, v97
	v_mul_f32_e32 v67, 0x4b800000, v66
	v_cmp_gt_f32_e32 vcc, s1, v66
	v_mul_f32_e32 v217, v8, v156
	v_mul_f32_e32 v218, v9, v157
	v_cndmask_b32_e32 v66, v66, v67, vcc
	v_rsq_f32_e32 v66, v66
	v_mul_f32_e32 v158, v2, v158
	v_mul_f32_e32 v159, v3, v159
	v_mul_f32_e32 v160, v4, v160
	v_mul_f32_e32 v67, 0x45800000, v66
	v_cndmask_b32_e32 v66, v66, v67, vcc
	v_mul_f32_e32 v128, 0x41000000, v66
	v_mul_f32_e32 v67, v174, v66
	v_mul_f32_e32 v68, v175, v66
	v_mul_f32_e32 v174, v174, v128
	v_mul_f32_e32 v175, v175, v128
	v_cvt_pk_fp8_f32 v98, v174, v175
	v_mul_f32_e32 v71, v178, v66
	v_mul_f32_e32 v72, v179, v66
	v_mul_f32_e32 v178, v178, v128
	v_mul_f32_e32 v179, v179, v128
	v_mul_f32_e32 v161, v5, v161
	v_mul_f32_e32 v69, v176, v66
	v_mul_f32_e32 v70, v177, v66
	v_mul_f32_e32 v73, v180, v66
	v_mul_f32_e32 v74, v181, v66
	v_mul_f32_e32 v75, v182, v66
	v_mul_f32_e32 v81, v188, v66
	v_mul_f32_e32 v88, v189, v66
	v_mul_f32_e32 v114, v170, v66
	v_mul_f32_e32 v116, v173, v66
	v_mul_f32_e32 v138, v199, v66
	v_mul_f32_e32 v139, v129, v66
	v_mul_f32_e32 v140, v206, v66
	v_mul_f32_e32 v141, v207, v66
	v_mul_f32_e32 v144, v130, v66
	v_mul_f32_e32 v145, v131, v66
	v_mul_f32_e32 v156, v134, v66
	v_mul_f32_e32 v157, v135, v66
	v_cvt_pk_fp8_f32 v99, v178, v179
	v_mul_f32_e32 v76, v183, v66
	v_mul_f32_e32 v77, v184, v66
	v_mul_f32_e32 v78, v185, v66
	v_mul_f32_e32 v79, v186, v66
	v_mul_f32_e32 v80, v187, v66
	v_mul_f32_e32 v89, v168, v66
	v_mul_f32_e32 v115, v172, v66
	v_mul_f32_e32 v117, v190, v66
	v_mul_f32_e32 v118, v191, v66
	v_mul_f32_e32 v119, v192, v66
	v_mul_f32_e32 v120, v193, v66
	v_mul_f32_e32 v121, v194, v66
	v_mul_f32_e32 v122, v195, v66
	v_mul_f32_e32 v123, v196, v66
	v_mul_f32_e32 v124, v197, v66
	v_mul_f32_e32 v125, v198, v66
	v_mul_f32_e32 v126, v127, v66
	v_mul_f32_e32 v142, v208, v66
	v_mul_f32_e32 v143, v209, v66
	v_mul_f32_e32 v154, v132, v66
	v_mul_f32_e32 v155, v133, v66
	v_mul_f32_e32 v162, v136, v66
	v_mul_f32_e32 v163, v137, v66
	v_mul_f32_e32 v164, v210, v66
	v_mul_f32_e32 v165, v211, v66
	v_mul_f32_e32 v166, v213, v66
	v_mul_f32_e32 v167, v214, v66
	v_mul_f32_e32 v169, v146, v66
; __device__ __forceinline__ void p0_prologue(const Ptrs& P, LAS unsigned char* lds, int vcu, int G, int tid) {
;     ...
;         for (int m = gw; m < T; m += NGW) {
;             const f32x4* xr = (const f32x4*)(P.x + (size_t)m * D) + lane;
;             f32x4 v[16]; float s = 0.f;
; #pragma unroll
;             for (int j = 0; j < 16; ++j) v[j] = __builtin_nontemporal_load(xr + 64 * j);
; #pragma unroll
;             for (int j = 0; j < 16; ++j) s += (v[j][0] * v[j][0] + v[j][1] * v[j][1]) + (v[j][2] * v[j][2] + v[j][3] * v[j][3]);
;             const float rs = rsqrtf(wave_sum(s) * (1.f / D) + EPS), s8 = rs * F8_SU;
;             u32x2* o = (u32x2*)(P.U + (size_t)m * D) + lane;
;             unsigned* o8 = (unsigned*)(P.U8 + (size_t)m * D) + lane;
; #pragma unroll
;             for (int j = 0; j < 16; ++j) { const f32x4 w = nwv[j]; const float a0 = v[j][0] * w[0], a1 = v[j][1] * w[1], a2 = v[j][2] * w[2], a3 = v[j][3] * w[3];
;                 u32x2 q; q.x = pkg(a0 * rs, a1 * rs); q.y = pkg(a2 * rs, a3 * rs); o[64 * j] = q;
;                 int w8 = 0; w8 = __builtin_amdgcn_cvt_pk_fp8_f32(a0 * s8, a1 * s8, w8, false); w8 = __builtin_amdgcn_cvt_pk_fp8_f32(a2 * s8, a3 * s8, w8, true); o8[64 * j] = (unsigned)w8; }
;         }
	v_mul_f32_e32 v171, v147, v66
	v_mul_f32_e32 v200, v148, v66
	v_mul_f32_e32 v201, v149, v66
	v_mul_f32_e32 v202, v150, v66
	v_mul_f32_e32 v203, v151, v66
	v_mul_f32_e32 v204, v152, v66
	v_mul_f32_e32 v205, v153, v66
	v_mul_f32_e32 v219, v215, v66
	v_mul_f32_e32 v220, v216, v66
	v_mul_f32_e32 v221, v217, v66
	v_mul_f32_e32 v222, v218, v66
	v_mul_f32_e32 v223, v158, v66
	v_mul_f32_e32 v224, v159, v66
	v_mul_f32_e32 v225, v160, v66
	v_mul_f32_e32 v226, v161, v66
	v_cvt_pk_bf16_f32 v66, v67, v68
	v_cvt_pk_bf16_f32 v67, v69, v70
	v_mul_f32_e32 v176, v176, v128
	v_mul_f32_e32 v177, v177, v128
	v_cvt_pk_bf16_f32 v69, v73, v74
	v_cvt_pk_bf16_f32 v70, v75, v76
	v_mul_f32_e32 v182, v182, v128
	v_mul_f32_e32 v183, v183, v128
	v_cvt_pk_bf16_f32 v73, v81, v88
	v_mul_f32_e32 v186, v186, v128
	v_mul_f32_e32 v187, v187, v128
	v_cvt_pk_bf16_f32 v74, v89, v114
	v_cvt_pk_bf16_f32 v75, v115, v116
	v_mul_f32_e32 v168, v168, v128
	v_mul_f32_e32 v170, v170, v128
	v_mul_f32_e32 v190, v190, v128
	v_mul_f32_e32 v191, v191, v128
	v_mul_f32_e32 v194, v194, v128
	v_mul_f32_e32 v195, v195, v128
	v_cvt_pk_bf16_f32 v81, v138, v139
	v_mul_f32_e32 v138, v198, v128
	v_mul_f32_e32 v139, v127, v128
	v_cvt_pk_bf16_f32 v88, v140, v141
	v_mul_f32_e32 v140, v206, v128
	v_mul_f32_e32 v141, v207, v128
	v_cvt_pk_bf16_f32 v114, v144, v145
	v_mul_f32_e32 v130, v130, v128
	v_mul_f32_e32 v131, v131, v128
	v_cvt_pk_bf16_f32 v116, v156, v157
	v_mul_f32_e32 v134, v134, v128
	v_mul_f32_e32 v135, v135, v128
	v_mul_f32_e32 v144, v210, v128
	v_mul_f32_e32 v145, v211, v128
	v_mul_f32_e32 v146, v146, v128
	v_mul_f32_e32 v147, v147, v128
	v_mul_f32_e32 v150, v150, v128
	v_mul_f32_e32 v151, v151, v128
	v_mul_f32_e32 v156, v215, v128
	v_mul_f32_e32 v157, v216, v128
	v_mul_f32_e32 v158, v158, v128
	v_mul_f32_e32 v159, v159, v128
	v_cvt_pk_fp8_f32 v100, v182, v183
	v_cvt_pk_fp8_f32 v101, v186, v187
	v_cvt_pk_fp8_f32 v102, v168, v170
	v_cvt_pk_fp8_f32 v103, v190, v191
	v_cvt_pk_fp8_f32 v104, v194, v195
	v_cvt_pk_fp8_f32 v105, v138, v139
	v_cvt_pk_fp8_f32 v106, v140, v141
	v_cvt_pk_fp8_f32 v107, v130, v131
	v_cvt_pk_fp8_f32 v108, v134, v135
	v_cvt_pk_fp8_f32 v109, v144, v145
	v_cvt_pk_fp8_f32 v110, v146, v147
	v_cvt_pk_fp8_f32 v111, v150, v151
	v_cvt_pk_fp8_f32 v112, v156, v157
	v_cvt_pk_fp8_f32 v113, v158, v159
	v_cvt_pk_fp8_f32 v98, v176, v177 op_sel:[0,0,1]
	v_mul_f32_e32 v180, v180, v128
	v_mul_f32_e32 v181, v181, v128
	v_cvt_pk_fp8_f32 v99, v180, v181 op_sel:[0,0,1]
	v_mul_f32_e32 v184, v184, v128
	v_mul_f32_e32 v185, v185, v128
	v_mul_f32_e32 v188, v188, v128
	v_mul_f32_e32 v189, v189, v128
	v_mul_f32_e32 v172, v172, v128
	v_mul_f32_e32 v173, v173, v128
	v_cvt_pk_bf16_f32 v76, v117, v118
	v_mul_f32_e32 v192, v192, v128
	v_mul_f32_e32 v193, v193, v128
	v_mul_f32_e32 v196, v196, v128
	v_mul_f32_e32 v197, v197, v128
	v_mul_f32_e32 v198, v199, v128
	v_mul_f32_e32 v129, v129, v128
	v_cvt_pk_bf16_f32 v89, v142, v143
	v_mul_f32_e32 v142, v208, v128
	v_mul_f32_e32 v143, v209, v128
	v_cvt_pk_bf16_f32 v115, v154, v155
	v_mul_f32_e32 v132, v132, v128
	v_mul_f32_e32 v133, v133, v128
	v_cvt_pk_bf16_f32 v117, v162, v163
	v_mul_f32_e32 v136, v136, v128
	v_mul_f32_e32 v137, v137, v128
	v_mul_f32_e32 v154, v213, v128
	v_mul_f32_e32 v155, v214, v128
	v_mul_f32_e32 v148, v148, v128
	v_mul_f32_e32 v149, v149, v128
	v_mul_f32_e32 v152, v152, v128
	v_mul_f32_e32 v153, v153, v128
	v_mul_f32_e32 v162, v217, v128
	v_mul_f32_e32 v163, v218, v128
	v_mul_f32_e32 v160, v160, v128
	v_mul_f32_e32 v128, v161, v128
	v_cvt_pk_bf16_f32 v68, v71, v72
	v_cvt_pk_bf16_f32 v71, v77, v78
	v_cvt_pk_bf16_f32 v72, v79, v80
	v_cvt_pk_bf16_f32 v77, v119, v120
	v_cvt_pk_bf16_f32 v78, v121, v122
	v_cvt_pk_bf16_f32 v79, v123, v124
	v_cvt_pk_bf16_f32 v80, v125, v126
	v_cvt_pk_bf16_f32 v118, v164, v165
	v_cvt_pk_bf16_f32 v119, v166, v167
	v_cvt_pk_bf16_f32 v120, v169, v171
	v_cvt_pk_bf16_f32 v121, v200, v201
	v_cvt_pk_bf16_f32 v122, v202, v203
	v_cvt_pk_bf16_f32 v123, v204, v205
	v_cvt_pk_bf16_f32 v124, v219, v220
	v_cvt_pk_bf16_f32 v125, v221, v222
	v_cvt_pk_bf16_f32 v126, v223, v224
	v_cvt_pk_bf16_f32 v127, v225, v226
	global_store_dwordx2 v[86:87], v[66:67], off offset:-4096 sc1
	v_cvt_pk_fp8_f32 v100, v184, v185 op_sel:[0,0,1]
	v_cvt_pk_fp8_f32 v101, v188, v189 op_sel:[0,0,1]
	v_cvt_pk_fp8_f32 v102, v172, v173 op_sel:[0,0,1]
	v_cvt_pk_fp8_f32 v103, v192, v193 op_sel:[0,0,1]
	v_cvt_pk_fp8_f32 v104, v196, v197 op_sel:[0,0,1]
	v_cvt_pk_fp8_f32 v105, v198, v129 op_sel:[0,0,1]
	v_cvt_pk_fp8_f32 v106, v142, v143 op_sel:[0,0,1]
	v_cvt_pk_fp8_f32 v107, v132, v133 op_sel:[0,0,1]
	v_cvt_pk_fp8_f32 v108, v136, v137 op_sel:[0,0,1]
	v_cvt_pk_fp8_f32 v109, v154, v155 op_sel:[0,0,1]
	v_cvt_pk_fp8_f32 v110, v148, v149 op_sel:[0,0,1]
	v_cvt_pk_fp8_f32 v111, v152, v153 op_sel:[0,0,1]
	v_cvt_pk_fp8_f32 v112, v162, v163 op_sel:[0,0,1]
	v_cvt_pk_fp8_f32 v113, v160, v128 op_sel:[0,0,1]
	global_store_dword v[84:85], v98, off offset:-2048 sc1
	global_store_dwordx2 v[86:87], v[68:69], off offset:-3584 sc1
	global_store_dword v[84:85], v99, off offset:-1792 sc1
	global_store_dwordx2 v[86:87], v[70:71], off offset:-3072 sc1
	global_store_dword v[84:85], v100, off offset:-1536 sc1
	global_store_dwordx2 v[86:87], v[72:73], off offset:-2560 sc1
	global_store_dword v[84:85], v101, off offset:-1280 sc1
	global_store_dwordx2 v[86:87], v[74:75], off offset:-2048 sc1
	global_store_dword v[84:85], v102, off offset:-1024 sc1
	global_store_dwordx2 v[86:87], v[76:77], off offset:-1536 sc1
	global_store_dword v[84:85], v103, off offset:-768 sc1
	global_store_dwordx2 v[86:87], v[78:79], off offset:-1024 sc1
	global_store_dword v[84:85], v104, off offset:-512 sc1
	global_store_dwordx2 v[86:87], v[80:81], off offset:-512 sc1
	global_store_dword v[84:85], v105, off offset:-256 sc1
	global_store_dwordx2 v[86:87], v[88:89], off sc1
	global_store_dword v[84:85], v106, off sc1
	global_store_dwordx2 v[86:87], v[114:115], off offset:512 sc1
	global_store_dword v[84:85], v107, off offset:256 sc1
	global_store_dwordx2 v[86:87], v[116:117], off offset:1024 sc1
	global_store_dword v[84:85], v108, off offset:512 sc1
	global_store_dwordx2 v[86:87], v[118:119], off offset:1536 sc1
	global_store_dword v[84:85], v109, off offset:768 sc1
	global_store_dwordx2 v[86:87], v[120:121], off offset:2048 sc1
	global_store_dword v[84:85], v110, off offset:1024 sc1
	global_store_dwordx2 v[86:87], v[122:123], off offset:2560 sc1
	global_store_dword v[84:85], v111, off offset:1280 sc1
	global_store_dwordx2 v[86:87], v[124:125], off offset:3072 sc1
	global_store_dword v[84:85], v112, off offset:1536 sc1
	global_store_dwordx2 v[86:87], v[126:127], off offset:3584 sc1
	global_store_dword v[84:85], v113, off offset:1792 sc1
	v_lshl_add_u64 v[84:85], v[84:85], 0, s[10:11]
	v_lshl_add_u64 v[86:87], v[86:87], 0, s[12:13]
	s_cbranch_scc0 .LBB0_67
